# diff_attn: items re-mapped so every CU processes all 8 heads (hd=(it+(it>>8))&7) + lazy O/l rescale (threshold 8 log2 units); balances the data-dependent rescale savings across CUs (stacked on v22)
# speedup vs baseline: 1.0021x; 1.0021x over previous
; #define LAS __attribute__((address_space(3)))
; DI f32x16 zero16() { f32x16 z; for (int i = 0; i < 16; ++i) z[i] = 0.f; return z; }
; DI void diff_attn_phase(int wv, LAS unsigned char* lds, const bf16_t* qk, const bf16_t* vt, bf16_t* ob, const float* lq1, const float* lk1, const float* lq2, const float* lk2,
;                         const float* subg, int layer_idx) {
;     ...
;         const int rho = it >> 8, j = it & 255, grp = j >> 6, bh = j & 63;
;         const int qb = 28 - 4 * rho + ((rho & 1) ? grp : 3 - grp);
;         const int b = bh >> 3, hd = bh & 7;
;         const int q0 = qb * 128 + qsub * 32, nkt = 2 * qb + 2, qpos = q0 + rr;
;         const float slope2 = exp2f(-(float)(hd + 1)) * LOG2E;
;         const bf16_t* qkb = qk + (size_t)b * SEQ * 2048;
;         LAS unsigned char* qlds = lds + 2 * DA_BUF + wid * 4096 + lane * 16;
; #pragma unroll
;         for (int ks = 0; ks < 4; ++ks) *(LAS bf16x8*)(qlds + ks * 1024) = *(const bf16x8*)(qkb + (size_t)(q0 + rr) * 2048 + hd * 128 + map * 64 + ks * 16 + hh * 8);
;         const bf16_t* kg = qkb + 1024 + hd * 128 + kch * 8 + (size_t)krow0 * 2048;
;         const bf16_t* vg = vt + (size_t)(hd * 128 + vrow0) * M_TOK + (size_t)b * SEQ + vch * 8;
;         float cb[16];
; #pragma unroll
;         for (int i = 0; i < 16; ++i) cb[i] = slope2 * (float)((i & 7) + 16 * (i >> 3));
;         f32x16 O[4];
; #pragma unroll
;         for (int d = 0; d < 4; ++d) O[d] = zero16();
;         float m = -INFINITY, l = 0.f;
;         if (!have_pf) {
; #pragma unroll
;             for (int i = 0; i < 2; ++i) { gk[i] = *(const u32x4*)(kg + (size_t)i * 32 * 2048); gv[i] = *(const u32x4*)(vg + (size_t)i * 64 * M_TOK); } }
; #pragma unroll
;         for (int i = 0; i < 2; ++i) { *(LAS u32x4*)(lds + kst_off + i * 32 * DA_KP) = gk[i]; *(LAS u32x4*)(lds + vst_off + i * 64 * DA_VP) = gv[i]; }
.LBB0_420:
	s_bfe_u32 s0, s18, 0x20006
	s_ashr_i32 s1, s18, 6
	s_and_b32 s2, s1, -4
	s_and_b32 s3, s18, 0x100
	s_xor_b32 s14, s0, 3
	s_cmp_eq_u32 s3, 0
	s_cselect_b32 s14, s14, s0
	s_sub_i32 s15, s14, s2
	s_add_i32 s15, s15, 28
	s_lshl_b32 s2, s18, 9
	s_lshl_b32 s0, s15, 7
	s_and_b32 s23, s2, 0x7000
	s_lshr_b32 s16, s18, 8
	s_add_i32 s16, s16, s18
	s_and_b32 s16, s16, 7
	s_or_b32 s22, s0, s19
	s_lshl_b32 s2, s23, 12
	v_or_b32_e32 v162, s22, v147
	s_add_u32 s26, s72, s2
	v_mov_b32_e32 v163, v1
	s_addc_u32 s27, s73, 0
	v_lshlrev_b64 v[2:3], 12, v[162:163]
	v_lshl_add_u64 v[2:3], s[26:27], 0, v[2:3]
	s_lshl_b32 s56, s16, 8
	v_lshl_add_u64 v[2:3], v[2:3], 0, s[56:57]
	v_lshl_add_u64 v[2:3], s[4:5], 1, v[2:3]
	v_mov_b32_e32 v157, v1
	v_lshl_add_u64 v[6:7], v[2:3], 0, v[156:157]
	global_load_dwordx4 v[2:5], v[6:7], off
	global_load_dwordx4 v[8:11], v[6:7], off offset:32
	global_load_dwordx4 v[12:15], v[6:7], off offset:64
	global_load_dwordx4 v[16:19], v[6:7], off offset:96
	s_lshl_b32 s24, s16, 7
	s_add_u32 s26, s26, s56
	s_addc_u32 s27, s27, 0
	v_lshlrev_b32_e32 v164, 1, v148
	v_mov_b32_e32 v165, v1
	s_lshl_b32 s56, s23, 1
	v_lshlrev_b32_e32 v190, 1, v152
	v_mov_b32_e32 v191, v1
	s_and_b64 vcc, exec, s[12:13]
	s_waitcnt vmcnt(0)
	ds_write_b128 v217, v[2:5]
	ds_write_b128 v217, v[8:11] offset:1024
	ds_write_b128 v217, v[12:15] offset:2048
	ds_write_b128 v217, v[16:19] offset:3072
	v_add_u32_e32 v4, s24, v161
	v_ashrrev_i32_e32 v5, 31, v4
	v_lshlrev_b64 v[4:5], 16, v[4:5]
	v_lshl_add_u64 v[4:5], s[78:79], 0, v[4:5]
	v_lshl_add_u64 v[2:3], s[26:27], 0, v[164:165]
	v_lshl_add_u64 v[4:5], v[4:5], 0, s[56:57]
	v_lshl_add_u64 v[114:115], v[150:151], 1, v[2:3]
	v_lshl_add_u64 v[116:117], v[4:5], 0, v[190:191]
	s_cbranch_vccnz .LBB0_422
	v_add_co_u32_e32 v2, vcc, 0x20000, v114
	global_load_dwordx4 v[102:105], v[114:115], off offset:2048
	global_load_dwordx4 v[98:101], v[116:117], off
	v_addc_co_u32_e32 v3, vcc, 0, v115, vcc
	v_add_co_u32_e32 v4, vcc, 0x400000, v116
	s_nop 1
	v_addc_co_u32_e32 v5, vcc, 0, v117, vcc
	global_load_dwordx4 v[106:109], v[2:3], off offset:2048
	global_load_dwordx4 v[110:113], v[4:5], off

; #define LAS __attribute__((address_space(3)))
; DI void diff_attn_phase(int wv, LAS unsigned char* lds, const bf16_t* qk, const bf16_t* vt, bf16_t* ob, const float* lq1, const float* lk1, const float* lq2, const float* lk2,
;                         const float* subg, int layer_idx) {
;     ...
;             else if (it + (int)gridDim.x < 2048) {
;                 const int itn = it + (int)gridDim.x, bhn = itn & 63, bn = bhn >> 3, hdn = bhn & 7;
;                 const bf16_t* kgn = qk + (size_t)bn * SEQ * 2048 + 1024 + hdn * 128 + kch * 8 + (size_t)krow0 * 2048;
;                 const bf16_t* vgn = vt + (size_t)(hdn * 128 + vrow0) * M_TOK + (size_t)bn * SEQ + vch * 8;
; #pragma unroll
;                 for (int i = 0; i < 2; ++i) { gk[i] = *(const u32x4*)(kgn + (size_t)i * 32 * 2048); gv[i] = *(const u32x4*)(vgn + (size_t)i * 64 * M_TOK); }
;                 have_pf = true; }
;     ...
;             if (more) {
;                 LAS unsigned char* nb = lds + ((t + 1) & 1) * DA_BUF;
; #pragma unroll
;                 for (int i = 0; i < 2; ++i) { *(LAS u32x4*)(nb + kst_off + i * 32 * DA_KP) = gk[i]; *(LAS u32x4*)(nb + vst_off + i * 64 * DA_VP) = gv[i]; } }
;             __syncthreads();
.LBB0_431:
	s_add_i32 s18, s20, s18
	s_cmpk_gt_i32 s18, 0x7ff
	s_cselect_b64 s[14:15], -1, 0
	s_and_b64 vcc, exec, s[14:15]
	s_waitcnt vmcnt(3)
	ds_write_b128 v163, v[102:105] offset:35840
	s_waitcnt vmcnt(2)
	ds_write_b128 v165, v[98:101] offset:53248
	s_waitcnt vmcnt(1)
	ds_write_b128 v163, v[106:109] offset:44544
	s_waitcnt vmcnt(0)
	ds_write_b128 v165, v[110:113] offset:62464
	s_waitcnt lgkmcnt(0)
	s_barrier
	s_cbranch_vccnz .LBB0_433
	s_lshl_b32 s0, s18, 9
	s_and_b32 s0, s0, 0x7000
	s_lshl_b32 s2, s0, 12
	s_add_u32 s2, s72, s2
	s_addc_u32 s3, s73, 0
	s_lshr_b32 s12, s18, 8
	s_add_i32 s12, s12, s18
	s_lshl_b32 s12, s12, 7
	s_and_b32 s17, s12, 0x380
	s_lshl_b32 s12, s17, 1
	v_add_u32_e32 v68, s17, v161
	s_add_u32 s12, s2, s12
	v_ashrrev_i32_e32 v69, 31, v68
	s_addc_u32 s13, s3, 0
	v_mov_b32_e32 v165, v1
	v_lshlrev_b64 v[68:69], 16, v[68:69]
	v_lshl_add_u64 v[66:67], s[12:13], 0, v[164:165]
	v_lshl_add_u64 v[68:69], s[78:79], 0, v[68:69]
	s_lshl_b32 s56, s0, 1
	v_lshl_add_u64 v[66:67], v[150:151], 1, v[66:67]
	v_lshl_add_u64 v[68:69], v[68:69], 0, s[56:57]
	v_mov_b32_e32 v191, v1
	v_lshl_add_u64 v[68:69], v[68:69], 0, v[190:191]
	global_load_dwordx4 v[102:105], v[66:67], off offset:2048
	global_load_dwordx4 v[98:101], v[68:69], off
	v_add_co_u32_e32 v66, vcc, 0x20000, v66
	s_mov_b64 s[12:13], -1
	s_nop 0
	v_addc_co_u32_e32 v67, vcc, 0, v67, vcc
	v_add_co_u32_e32 v68, vcc, 0x400000, v68
	s_nop 1
	v_addc_co_u32_e32 v69, vcc, 0, v69, vcc
	global_load_dwordx4 v[106:109], v[66:67], off offset:2048
	global_load_dwordx4 v[110:113], v[68:69], off
